# filler balance, second pass: G3 tails back to OUT|GU2|D2 (they have the longest slot), hl=1 tail GU1(l1) only, hl=2 tail D1(l1)|IN(l1)|KV(l1), hl=3 tail empty, so every tail slot keeps several microse
# speedup vs baseline: 1.0152x; 1.0036x over previous
.LBB0_127:
	v_readlane_b32 s4, v253, 12
	v_readlane_b32 s5, v253, 13
	s_mov_b64 s[0:1], s[76:77]
	v_mov_b32_e32 v0, v204
	s_andn2_b64 vcc, exec, s[4:5]
	s_cbranch_vccnz .LBB0_251
	v_ashrrev_i32_e32 v2, 6, v0
	v_readlane_b32 s4, v253, 14
	s_nop 1
	v_add_u32_e32 v11, s4, v2
	s_movk_i32 s96, 0x2b00
	s_movk_i32 s97, 0xa00
	s_cmp_eq_u32 s75, 3
	s_cselect_b32 s96, 0, s96
	s_cselect_b32 s97, 0x7fffffff, s97
	v_cmp_gt_i32_e32 vcc, s96, v11
	s_and_saveexec_b64 s[24:25], vcc
	s_cbranch_execz .LBB0_250
	v_and_b32_e32 v10, 63, v0
	v_bfe_u32 v12, v0, 3, 3
	v_lshlrev_b32_e32 v3, 2, v0
	v_lshlrev_b32_e32 v0, 3, v0
	v_and_b32_e32 v14, 28, v3
	s_movk_i32 s4, 0x84
	v_mov_b32_e32 v3, 0x840
	v_and_b32_e32 v16, 56, v0
	v_lshl_add_u32 v2, v2, 14, 0
	v_mad_u32_u24 v29, v12, s4, v3
	v_mul_u32_u24_e32 v0, 0x84, v16
	v_lshlrev_b32_e32 v3, 2, v12
	v_lshl_add_u32 v15, v14, 2, v2
	v_mul_u32_u24_e32 v17, 0x84, v12
	v_or_b32_e32 v26, 8, v12
	v_mad_u32_u24 v27, v12, s4, v252
	v_or_b32_e32 v28, 16, v12
	v_or_b32_e32 v30, 24, v12
	v_or_b32_e32 v31, 32, v12
	v_or_b32_e32 v32, 40, v12
	v_or_b32_e32 v33, 48, v12
	v_or_b32_e32 v34, 56, v12
	v_add3_u32 v35, v2, v0, v3
	v_mov_b32_e32 v13, v1
	s_mov_b64 s[46:47], 0
	s_branch .LBB0_134

.LBB0_377:
	s_andn2_b64 vcc, exec, s[0:1]
	s_cbranch_vccnz .LBB0_463
	s_mov_b64 s[0:1], s[76:77]
	v_mov_b32_e32 v0, v204
	s_and_b64 vcc, exec, s[38:39]
	s_cbranch_vccnz .LBB0_463
	v_ashrrev_i32_e32 v2, 6, v0
	v_readlane_b32 s4, v253, 14
	s_nop 1
	v_add_u32_e32 v13, s4, v2
	s_movk_i32 s4, 0xb00
	v_cmp_gt_i32_e32 vcc, s4, v13
	s_and_saveexec_b64 s[24:25], vcc
	s_cbranch_execz .LBB0_462
	v_lshlrev_b32_e32 v3, 2, v0
	v_bfe_u32 v10, v0, 3, 3
	v_and_b32_e32 v12, 28, v3
	s_movk_i32 s4, 0x84
	v_mov_b32_e32 v3, 0x840
	v_mad_u32_u24 v26, v10, s4, v252
	v_mad_u32_u24 v28, v10, s4, v3
	s_load_dwordx2 s[4:5], s[0:1], 0xd0
	v_lshlrev_b32_e32 v0, 3, v0
	v_and_b32_e32 v14, 56, v0
	v_lshl_add_u32 v2, v2, 14, 0
	v_mul_u32_u24_e32 v0, 0x84, v14
	v_lshlrev_b32_e32 v3, 2, v10
	s_waitcnt lgkmcnt(0)
	s_add_u32 s46, s4, 0x100000
	v_lshl_add_u32 v15, v12, 2, v2
	v_mul_u32_u24_e32 v24, 0x84, v10
	v_or_b32_e32 v25, 8, v10
	v_or_b32_e32 v27, 16, v10
	v_or_b32_e32 v29, 24, v10
	v_or_b32_e32 v30, 32, v10
	v_or_b32_e32 v31, 40, v10
	v_or_b32_e32 v32, 48, v10
	v_or_b32_e32 v33, 56, v10
	v_add3_u32 v34, v2, v0, v3
	s_addc_u32 s47, s5, 0
	v_mov_b32_e32 v11, v1
	s_mov_b64 s[48:49], 0
	s_branch .LBB0_383

.LBB0_382:
	s_or_b64 exec, exec, s[50:51]
	v_add_u32_e32 v13, s95, v13
	s_movk_i32 s4, 0xaff
	v_cmp_lt_i32_e32 vcc, s4, v13
	s_or_b64 s[48:49], vcc, s[48:49]
	s_andn2_b64 exec, exec, s[48:49]
	s_cbranch_execz .LBB0_462
